# diff-attn unit epilogue: all gate / sub-norm gain loads hoisted ahead of the 16-segment waterfall
# baseline (speedup 1.0000x reference)
; __device__ __forceinline__ float half_sum(float m) { auto rr = __builtin_amdgcn_permlane32_swap(__float_as_uint(m), __float_as_uint(m), false, false); return __uint_as_float(rr[0]) + __uint_as_float(rr[1]); }
; __device__ __forceinline__ int lane_now() { int l; asm volatile("v_mbcnt_lo_u32_b32 %0, -1, 0\n\tv_mbcnt_hi_u32_b32 %0, -1, %0" : "=v"(l)); return l; }
; template <bool FIXM> __device__ __forceinline__ void diff_unit(int b, int h, int qb, float lam, const bf16* U, const bf16* VTa, bf16* Y, const float* subg, const float* qgain, const int* pos, unsigned char* lds, int tid, int wid, int lane) {
;     ...
;     float ss = 0.f;
; #pragma unroll
;     for (int db = 0; db < 4; ++db)
; #pragma unroll
;         for (int r = 0; r < 16; ++r) ss += o[db][r] * o[db][r];
;     ss = half_sum(ss);
;     const float rstd = 0.8f / sqrtf(ss * (1.f / 128.f) + EPS);
;     const int lane_e = lane_now();
;     const int hi_e = lane_e >> 5, tq_e = t0 + (lane_e & 31);
;     const bf16* gar = U + (rowbase + tq_e) * EU + C_GA + h * 128;
;     bf16* yr = Y + (rowbase + tq_e) * D + h * 128; u32x2 wprev = {0u, 0u};
; #pragma unroll
;     for (int db = 0; db < 4; ++db)
; #pragma unroll
;         for (int g4 = 0; g4 < 4; ++g4) {
;             const int e = 32 * db + 8 * g4 + 4 * hi_e;
;             const u32x2 gw = *(const u32x2*)(gar + e); const f32x4 sg = *(const f32x4*)(subg + e);
.LBB0_377:
	v_mul_f32_e32 v0, v115, v115
	v_fmac_f32_e32 v0, v114, v114
	v_fmac_f32_e32 v0, v116, v116
	v_fmac_f32_e32 v0, v117, v117
	v_fmac_f32_e32 v0, v118, v118
	v_fmac_f32_e32 v0, v119, v119
	v_fmac_f32_e32 v0, v120, v120
	v_fmac_f32_e32 v0, v121, v121
	v_fmac_f32_e32 v0, v122, v122
	v_fmac_f32_e32 v0, v123, v123
	v_fmac_f32_e32 v0, v124, v124
	v_fmac_f32_e32 v0, v125, v125
	v_fmac_f32_e32 v0, v126, v126
	v_fmac_f32_e32 v0, v127, v127
	v_fmac_f32_e32 v0, v128, v128
	v_fmac_f32_e32 v0, v129, v129
	v_fmac_f32_e32 v0, v34, v34
	v_fmac_f32_e32 v0, v35, v35
	v_fmac_f32_e32 v0, v36, v36
	v_fmac_f32_e32 v0, v37, v37
	v_fmac_f32_e32 v0, v38, v38
	v_fmac_f32_e32 v0, v39, v39
	v_fmac_f32_e32 v0, v40, v40
	v_fmac_f32_e32 v0, v41, v41
	v_fmac_f32_e32 v0, v42, v42
	v_fmac_f32_e32 v0, v43, v43
	v_fmac_f32_e32 v0, v44, v44
	v_fmac_f32_e32 v0, v45, v45
	v_fmac_f32_e32 v0, v46, v46
	v_fmac_f32_e32 v0, v47, v47
	v_fmac_f32_e32 v0, v48, v48
	v_fmac_f32_e32 v0, v49, v49
	v_fmac_f32_e32 v0, v18, v18
	v_fmac_f32_e32 v0, v19, v19
	v_fmac_f32_e32 v0, v20, v20
	v_fmac_f32_e32 v0, v21, v21
	v_fmac_f32_e32 v0, v22, v22
	v_fmac_f32_e32 v0, v23, v23
	v_fmac_f32_e32 v0, v24, v24
	v_fmac_f32_e32 v0, v25, v25
	v_fmac_f32_e32 v0, v26, v26
	v_fmac_f32_e32 v0, v27, v27
	v_fmac_f32_e32 v0, v28, v28
	v_fmac_f32_e32 v0, v29, v29
	v_fmac_f32_e32 v0, v30, v30
	v_fmac_f32_e32 v0, v31, v31
	v_fmac_f32_e32 v0, v32, v32
	v_fmac_f32_e32 v0, v33, v33
	v_fmac_f32_e32 v0, v2, v2
	v_fmac_f32_e32 v0, v3, v3
	v_fmac_f32_e32 v0, v4, v4
	v_fmac_f32_e32 v0, v5, v5
	v_fmac_f32_e32 v0, v6, v6
	v_fmac_f32_e32 v0, v7, v7
	v_fmac_f32_e32 v0, v8, v8
	v_fmac_f32_e32 v0, v9, v9
	v_fmac_f32_e32 v0, v10, v10
	v_fmac_f32_e32 v0, v11, v11
	v_fmac_f32_e32 v0, v12, v12
	v_fmac_f32_e32 v0, v13, v13
	v_fmac_f32_e32 v0, v14, v14
	v_fmac_f32_e32 v0, v15, v15
	v_pk_mul_f32 v[50:51], v[16:17], v[16:17]
	s_mov_b32 s0, 0xf800000
	v_add_f32_e32 v0, v50, v0
	v_add_f32_e32 v0, v51, v0
	v_mov_b32_e32 v50, v0
	s_nop 1
	v_permlane32_swap_b32_e32 v0, v50
	v_add_f32_e32 v0, v0, v50
	v_fmamk_f32 v0, v0, 0x3c000000, v223
	v_cmp_gt_f32_e32 vcc, s0, v0
	v_mul_f32_e32 v50, 0x4f800000, v0
	s_mov_b32 s2, 0x3f4ccccd
	v_cndmask_b32_e32 v0, v0, v50, vcc
	v_sqrt_f32_e32 v50, v0
	v_readlane_b32 s22, v251, 44
	v_readlane_b32 s23, v251, 45
	s_movk_i32 s20, 0x1600
	v_add_u32_e32 v51, -1, v50
	v_fma_f32 v52, -v51, v50, v0
	v_cmp_ge_f32_e64 s[0:1], 0, v52
	v_add_u32_e32 v52, 1, v50
	v_readlane_b32 s24, v251, 46
	v_cndmask_b32_e64 v51, v50, v51, s[0:1]
	v_fma_f32 v50, -v52, v50, v0
	v_cmp_lt_f32_e64 s[0:1], 0, v50
	v_readlane_b32 s25, v251, 47
	v_readlane_b32 s4, v252, 37
	v_cndmask_b32_e64 v50, v51, v52, s[0:1]
	v_mul_f32_e32 v51, 0x37800000, v50
	v_cndmask_b32_e32 v50, v50, v51, vcc
	v_cmp_class_f32_e32 vcc, v0, v224
	v_readlane_b32 s14, v252, 47
	v_readlane_b32 s15, v252, 48
	v_cndmask_b32_e32 v0, v50, v0, vcc
	v_div_scale_f32 v50, s[0:1], v0, v0, s2
	v_rcp_f32_e32 v51, v50
	v_readlane_b32 s0, v251, 50
	v_readlane_b32 s76, v251, 32
	v_readlane_b32 s77, v251, 33
	v_fma_f32 v52, -v50, v51, 1.0
	v_fmac_f32_e32 v51, v52, v51
	v_div_scale_f32 v52, vcc, s2, v0, s2
	v_mul_f32_e32 v53, v52, v51
	v_fma_f32 v54, -v50, v53, v52
	v_fmac_f32_e32 v53, v54, v51
	v_fma_f32 v50, -v50, v53, v52
	v_div_fmas_f32 v50, v50, v51, v53
	v_div_fixup_f32 v58, v50, v0, s2
	v_mbcnt_lo_u32_b32 v0, -1, 0
	v_mbcnt_hi_u32_b32 v0, -1, v0
	v_pk_mul_f32 v[68:69], v[114:115], v[58:59] op_sel_hi:[1,0]
	v_ashrrev_i32_e32 v55, 5, v0
	v_and_or_b32 v0, v0, 31, s0
	v_readlane_b32 s0, v251, 42
	v_readlane_b32 s1, v251, 43
	v_lshl_add_u64 v[50:51], s[22:23], 0, v[0:1]
	v_lshlrev_b32_e32 v54, 2, v55
	v_mov_b64_e32 v[52:53], s[0:1]
	v_mad_u64_u32 v[52:53], s[0:1], v50, s20, v[52:53]
	v_mad_i32_i24 v53, v51, s20, v53
	v_lshlrev_b64 v[50:51], 11, v[50:51]
	v_lshlrev_b32_e32 v56, 3, v55
	v_ashrrev_i32_e32 v55, 31, v54
	v_lshl_add_u64 v[50:51], s[24:25], 0, v[50:51]
	v_ashrrev_i32_e32 v57, 31, v56
	v_lshl_add_u64 v[62:63], v[54:55], 1, v[52:53]
	v_lshl_add_u64 v[60:61], v[56:57], 1, v[50:51]
	global_load_dwordx2 v[56:57], v[62:63], off offset:2048
	v_lshl_add_u64 v[64:65], v[54:55], 2, s[14:15]
	global_load_dwordx4 v[50:53], v[64:65], off
	global_load_dwordx4 v[160:163], v[64:65], off offset:32
	global_load_dwordx2 v[130:131], v[62:63], off offset:2064
	global_load_dwordx2 v[132:133], v[62:63], off offset:2080
	global_load_dwordx4 v[164:167], v[64:65], off offset:64
	global_load_dwordx4 v[168:171], v[64:65], off offset:96
	global_load_dwordx2 v[134:135], v[62:63], off offset:2096
	global_load_dwordx2 v[136:137], v[62:63], off offset:2112
	global_load_dwordx4 v[172:175], v[64:65], off offset:128
	global_load_dwordx4 v[176:179], v[64:65], off offset:160
	global_load_dwordx2 v[138:139], v[62:63], off offset:2128
	global_load_dwordx2 v[140:141], v[62:63], off offset:2144
	global_load_dwordx4 v[180:183], v[64:65], off offset:192
	global_load_dwordx4 v[184:187], v[64:65], off offset:224
	global_load_dwordx2 v[142:143], v[62:63], off offset:2160
	global_load_dwordx2 v[144:145], v[62:63], off offset:2176
	global_load_dwordx4 v[188:191], v[64:65], off offset:256
	global_load_dwordx4 v[192:195], v[64:65], off offset:288
	global_load_dwordx2 v[146:147], v[62:63], off offset:2192
	global_load_dwordx2 v[148:149], v[62:63], off offset:2208
	global_load_dwordx4 v[196:199], v[64:65], off offset:320
	global_load_dwordx4 v[200:203], v[64:65], off offset:352
	global_load_dwordx2 v[150:151], v[62:63], off offset:2224
	global_load_dwordx2 v[152:153], v[62:63], off offset:2240
	global_load_dwordx4 v[204:207], v[64:65], off offset:384
	global_load_dwordx4 v[208:211], v[64:65], off offset:416
; __device__ __forceinline__ unsigned cvtpk(float lo, float hi) { f32x2_t v = {lo, hi}; bf16x2_t b = __builtin_convertvector(v, bf16x2_t); return __builtin_bit_cast(unsigned, b); }
; __device__ __forceinline__ float bf_lo(unsigned w) { return __uint_as_float(w << 16); }
; __device__ __forceinline__ float bf_hi(unsigned w) { return __uint_as_float(w & 0xffff0000u); }
; __device__ __forceinline__ float silu_f(float x) { return x * __builtin_amdgcn_rcpf(1.f + __expf(-x)); }
; template <bool FIXM> __device__ __forceinline__ void diff_unit(int b, int h, int qb, float lam, const bf16* U, const bf16* VTa, bf16* Y, const float* subg, const float* qgain, const int* pos, unsigned char* lds, int tid, int wid, int lane) {
;     ...
; #pragma unroll
;     for (int db = 0; db < 4; ++db)
; #pragma unroll
;         for (int g4 = 0; g4 < 4; ++g4) {
;             const int e = 32 * db + 8 * g4 + 4 * hi_e;
;             const u32x2 gw = *(const u32x2*)(gar + e); const f32x4 sg = *(const f32x4*)(subg + e);
;             const float y0 = o[db][4 * g4 + 0] * rstd * sg.x * silu_f(bf_lo(gw.x)), y1 = o[db][4 * g4 + 1] * rstd * sg.y * silu_f(bf_hi(gw.x));
;             const float y2 = o[db][4 * g4 + 2] * rstd * sg.z * silu_f(bf_lo(gw.y)), y3 = o[db][4 * g4 + 3] * rstd * sg.w * silu_f(bf_hi(gw.y));
;             u32x2 w; w.x = cvtpk(y0, y1); w.y = cvtpk(y2, y3);
;             if ((g4 & 1) == 0) wprev = w; else store_pair16(yr + 32 * db + 16 * (g4 >> 1) + 8 * hi_e, wprev, w);
;         }
	global_load_dwordx2 v[154:155], v[62:63], off offset:2256
	global_load_dwordx2 v[156:157], v[62:63], off offset:2272
	global_load_dwordx4 v[212:215], v[64:65], off offset:448
	global_load_dwordx4 v[216:219], v[64:65], off offset:480
	global_load_dwordx2 v[158:159], v[62:63], off offset:2288
	v_pk_mul_f32 v[70:71], v[120:121], v[58:59] op_sel_hi:[1,0]
	v_pk_mul_f32 v[34:35], v[34:35], v[58:59] op_sel_hi:[1,0]
	v_pk_mul_f32 v[36:37], v[36:37], v[58:59] op_sel_hi:[1,0]
	v_pk_mul_f32 v[40:41], v[40:41], v[58:59] op_sel_hi:[1,0]
	v_pk_mul_f32 v[38:39], v[38:39], v[58:59] op_sel_hi:[1,0]
	v_pk_mul_f32 v[42:43], v[42:43], v[58:59] op_sel_hi:[1,0]
	v_pk_mul_f32 v[48:49], v[48:49], v[58:59] op_sel_hi:[1,0]
	v_pk_mul_f32 v[18:19], v[18:19], v[58:59] op_sel_hi:[1,0]
	v_pk_mul_f32 v[20:21], v[20:21], v[58:59] op_sel_hi:[1,0]
	v_pk_mul_f32 v[24:25], v[24:25], v[58:59] op_sel_hi:[1,0]
	v_pk_mul_f32 v[22:23], v[22:23], v[58:59] op_sel_hi:[1,0]
	v_pk_mul_f32 v[26:27], v[26:27], v[58:59] op_sel_hi:[1,0]
	v_pk_mul_f32 v[32:33], v[32:33], v[58:59] op_sel_hi:[1,0]
	v_pk_mul_f32 v[2:3], v[2:3], v[58:59] op_sel_hi:[1,0]
	v_pk_mul_f32 v[4:5], v[4:5], v[58:59] op_sel_hi:[1,0]
	v_pk_mul_f32 v[8:9], v[8:9], v[58:59] op_sel_hi:[1,0]
	v_pk_mul_f32 v[6:7], v[6:7], v[58:59] op_sel_hi:[1,0]
	v_pk_mul_f32 v[10:11], v[10:11], v[58:59] op_sel_hi:[1,0]
	v_pk_mul_f32 v[16:17], v[16:17], v[58:59] op_sel_hi:[1,0]
	v_readlane_b32 s0, v251, 51
	v_readlane_b32 s1, v251, 52
	v_readlane_b32 s5, v252, 38
	v_readlane_b32 s6, v252, 39
	v_readlane_b32 s7, v252, 40
	v_readlane_b32 s8, v252, 41
	v_readlane_b32 s9, v252, 42
	v_readlane_b32 s10, v252, 43
	v_readlane_b32 s11, v252, 44
	v_readlane_b32 s12, v252, 45
	v_readlane_b32 s13, v252, 46
	v_readlane_b32 s16, v252, 49
	v_readlane_b32 s17, v252, 50
	v_readlane_b32 s18, v252, 51
	v_readlane_b32 s19, v252, 52
	s_waitcnt vmcnt(0)
	v_lshlrev_b32_e32 v54, 16, v56
	v_mul_f32_e32 v0, 0xbfb8aa3b, v54
	v_exp_f32_e32 v0, v0
	v_and_b32_e32 v55, 0xffff0000, v56
	v_pk_mul_f32 v[50:51], v[50:51], v[68:69]
	v_add_f32_e32 v0, 1.0, v0
	v_rcp_f32_e32 v66, v0
	v_mul_f32_e32 v0, 0xbfb8aa3b, v55
	v_exp_f32_e32 v0, v0
	s_nop 0
	v_add_f32_e32 v0, 1.0, v0
	v_rcp_f32_e32 v67, v0
	s_nop 0
	v_pk_mul_f32 v[54:55], v[66:67], v[54:55]
	s_nop 0
	v_pk_mul_f32 v[50:51], v[50:51], v[54:55]
	v_lshlrev_b32_e32 v54, 16, v57
	v_mul_f32_e32 v0, 0xbfb8aa3b, v54
	v_exp_f32_e32 v0, v0
	v_and_b32_e32 v55, 0xffff0000, v57
	v_pk_mul_f32 v[66:67], v[116:117], v[58:59] op_sel_hi:[1,0]
	v_cvt_pk_bf16_f32 v50, v50, v51
	v_add_f32_e32 v0, 1.0, v0
	v_rcp_f32_e32 v56, v0
	v_mul_f32_e32 v0, 0xbfb8aa3b, v55
	v_exp_f32_e32 v0, v0
	v_pk_mul_f32 v[52:53], v[52:53], v[66:67]
	v_add_f32_e32 v0, 1.0, v0
	v_rcp_f32_e32 v57, v0
	s_nop 0
	v_pk_mul_f32 v[54:55], v[56:57], v[54:55]
	s_nop 0
	v_pk_mul_f32 v[52:53], v[52:53], v[54:55]
	s_nop 0
	v_cvt_pk_bf16_f32 v51, v52, v53
	v_mov_b64_e32 v[54:55], v[160:161]
	v_mov_b64_e32 v[56:57], v[162:163]
	v_mov_b64_e32 v[52:53], v[130:131]
	v_pk_mul_f32 v[56:57], v[56:57], v[70:71]
	v_lshlrev_b32_e32 v66, 16, v53
	v_mul_f32_e32 v0, 0xbfb8aa3b, v66
	v_exp_f32_e32 v0, v0
	v_and_b32_e32 v67, 0xffff0000, v53
	v_pk_mul_f32 v[70:71], v[128:129], v[58:59] op_sel_hi:[1,0]
	v_add_f32_e32 v0, 1.0, v0
	v_rcp_f32_e32 v68, v0
	v_mul_f32_e32 v0, 0xbfb8aa3b, v67
	v_exp_f32_e32 v0, v0
	s_nop 0
	v_add_f32_e32 v0, 1.0, v0
	v_rcp_f32_e32 v69, v0
	s_nop 0
	v_pk_mul_f32 v[66:67], v[68:69], v[66:67]
	s_nop 0
	v_pk_mul_f32 v[56:57], v[56:57], v[66:67]
	v_pk_mul_f32 v[68:69], v[118:119], v[58:59] op_sel_hi:[1,0]
	v_cvt_pk_bf16_f32 v53, v56, v57
	v_lshlrev_b32_e32 v56, 16, v52
	v_mul_f32_e32 v0, 0xbfb8aa3b, v56
	v_exp_f32_e32 v0, v0
	v_and_b32_e32 v57, 0xffff0000, v52
	v_pk_mul_f32 v[54:55], v[54:55], v[68:69]
	v_permlane32_swap_b32_e32 v51, v53
	v_add_f32_e32 v0, 1.0, v0
	v_rcp_f32_e32 v66, v0
	v_mul_f32_e32 v0, 0xbfb8aa3b, v57
	v_exp_f32_e32 v0, v0
	v_pk_mul_f32 v[68:69], v[122:123], v[58:59] op_sel_hi:[1,0]
	v_add_f32_e32 v0, 1.0, v0
	v_rcp_f32_e32 v67, v0
	s_nop 0
	v_pk_mul_f32 v[56:57], v[66:67], v[56:57]
	s_nop 0
	v_pk_mul_f32 v[54:55], v[54:55], v[56:57]
	s_nop 0
	v_cvt_pk_bf16_f32 v52, v54, v55
	s_nop 1
	v_permlane32_swap_b32_e32 v50, v52
	global_store_dwordx4 v[60:61], v[50:53], off
	s_nop 1
	v_mov_b64_e32 v[54:55], v[132:133]
	s_nop 0
	v_mov_b64_e32 v[50:51], v[164:165]
	v_mov_b64_e32 v[52:53], v[166:167]
	v_lshlrev_b32_e32 v56, 16, v54
	v_mul_f32_e32 v0, 0xbfb8aa3b, v56
	v_exp_f32_e32 v0, v0
	v_and_b32_e32 v57, 0xffff0000, v54
	v_lshlrev_b32_e32 v54, 16, v55
	v_pk_mul_f32 v[50:51], v[68:69], v[50:51]
	v_add_f32_e32 v0, 1.0, v0
	v_rcp_f32_e32 v66, v0
	v_mul_f32_e32 v0, 0xbfb8aa3b, v57
	v_exp_f32_e32 v0, v0
	v_and_b32_e32 v55, 0xffff0000, v55
	v_add_f32_e32 v0, 1.0, v0
	v_rcp_f32_e32 v67, v0
	v_mul_f32_e32 v0, 0xbfb8aa3b, v54
	v_exp_f32_e32 v0, v0
	v_pk_mul_f32 v[56:57], v[66:67], v[56:57]
	s_nop 0
	v_pk_mul_f32 v[50:51], v[50:51], v[56:57]
	v_add_f32_e32 v0, 1.0, v0
	v_rcp_f32_e32 v56, v0
	v_mul_f32_e32 v0, 0xbfb8aa3b, v55
	v_exp_f32_e32 v0, v0
	v_pk_mul_f32 v[66:67], v[124:125], v[58:59] op_sel_hi:[1,0]
	v_cvt_pk_bf16_f32 v50, v50, v51
	v_pk_mul_f32 v[52:53], v[66:67], v[52:53]
	v_add_f32_e32 v0, 1.0, v0
	v_rcp_f32_e32 v57, v0
	s_nop 0
	v_pk_mul_f32 v[54:55], v[56:57], v[54:55]
	s_nop 0
	v_pk_mul_f32 v[52:53], v[52:53], v[54:55]
	s_nop 0
	v_cvt_pk_bf16_f32 v51, v52, v53
	v_mov_b64_e32 v[54:55], v[168:169]
	v_mov_b64_e32 v[56:57], v[170:171]
	v_mov_b64_e32 v[52:53], v[134:135]
	v_pk_mul_f32 v[56:57], v[70:71], v[56:57]
	v_lshlrev_b32_e32 v66, 16, v53
	v_mul_f32_e32 v0, 0xbfb8aa3b, v66
	v_exp_f32_e32 v0, v0
	v_and_b32_e32 v67, 0xffff0000, v53
	v_add_f32_e32 v0, 1.0, v0
; __device__ __forceinline__ unsigned cvtpk(float lo, float hi) { f32x2_t v = {lo, hi}; bf16x2_t b = __builtin_convertvector(v, bf16x2_t); return __builtin_bit_cast(unsigned, b); }
; __device__ __forceinline__ float bf_lo(unsigned w) { return __uint_as_float(w << 16); }
; __device__ __forceinline__ float bf_hi(unsigned w) { return __uint_as_float(w & 0xffff0000u); }
; __device__ __forceinline__ float silu_f(float x) { return x * __builtin_amdgcn_rcpf(1.f + __expf(-x)); }
; template <bool FIXM> __device__ __forceinline__ void diff_unit(int b, int h, int qb, float lam, const bf16* U, const bf16* VTa, bf16* Y, const float* subg, const float* qgain, const int* pos, unsigned char* lds, int tid, int wid, int lane) {
;     ...
; #pragma unroll
;     for (int db = 0; db < 4; ++db)
; #pragma unroll
;         for (int g4 = 0; g4 < 4; ++g4) {
;             const int e = 32 * db + 8 * g4 + 4 * hi_e;
;             const u32x2 gw = *(const u32x2*)(gar + e); const f32x4 sg = *(const f32x4*)(subg + e);
;             const float y0 = o[db][4 * g4 + 0] * rstd * sg.x * silu_f(bf_lo(gw.x)), y1 = o[db][4 * g4 + 1] * rstd * sg.y * silu_f(bf_hi(gw.x));
;             const float y2 = o[db][4 * g4 + 2] * rstd * sg.z * silu_f(bf_lo(gw.y)), y3 = o[db][4 * g4 + 3] * rstd * sg.w * silu_f(bf_hi(gw.y));
;             u32x2 w; w.x = cvtpk(y0, y1); w.y = cvtpk(y2, y3);
;             if ((g4 & 1) == 0) wprev = w; else store_pair16(yr + 32 * db + 16 * (g4 >> 1) + 8 * hi_e, wprev, w);
;         }
	v_rcp_f32_e32 v68, v0
	v_mul_f32_e32 v0, 0xbfb8aa3b, v67
	v_exp_f32_e32 v0, v0
	s_nop 0
	v_add_f32_e32 v0, 1.0, v0
	v_rcp_f32_e32 v69, v0
	s_nop 0
	v_pk_mul_f32 v[66:67], v[68:69], v[66:67]
	s_nop 0
	v_pk_mul_f32 v[56:57], v[56:57], v[66:67]
	v_pk_mul_f32 v[68:69], v[126:127], v[58:59] op_sel_hi:[1,0]
	v_cvt_pk_bf16_f32 v53, v56, v57
	v_lshlrev_b32_e32 v56, 16, v52
	v_mul_f32_e32 v0, 0xbfb8aa3b, v56
	v_exp_f32_e32 v0, v0
	v_and_b32_e32 v57, 0xffff0000, v52
	v_pk_mul_f32 v[54:55], v[68:69], v[54:55]
	v_permlane32_swap_b32_e32 v51, v53
	v_add_f32_e32 v0, 1.0, v0
	v_rcp_f32_e32 v66, v0
	v_mul_f32_e32 v0, 0xbfb8aa3b, v57
	v_exp_f32_e32 v0, v0
	s_nop 0
	v_add_f32_e32 v0, 1.0, v0
	v_rcp_f32_e32 v67, v0
	s_nop 0
	v_pk_mul_f32 v[56:57], v[66:67], v[56:57]
	s_nop 0
	v_pk_mul_f32 v[54:55], v[54:55], v[56:57]
	s_nop 0
	v_cvt_pk_bf16_f32 v52, v54, v55
	s_nop 1
	v_permlane32_swap_b32_e32 v50, v52
	global_store_dwordx4 v[60:61], v[50:53], off offset:32
	s_nop 1
	v_mov_b64_e32 v[54:55], v[136:137]
	s_nop 0
	v_mov_b64_e32 v[50:51], v[172:173]
	v_mov_b64_e32 v[52:53], v[174:175]
	v_lshlrev_b32_e32 v56, 16, v54
	v_mul_f32_e32 v0, 0xbfb8aa3b, v56
	v_exp_f32_e32 v0, v0
	v_and_b32_e32 v57, 0xffff0000, v54
	v_pk_mul_f32 v[34:35], v[34:35], v[50:51]
	v_pk_mul_f32 v[36:37], v[36:37], v[52:53]
	v_add_f32_e32 v0, 1.0, v0
	v_rcp_f32_e32 v66, v0
	v_mul_f32_e32 v0, 0xbfb8aa3b, v57
	v_exp_f32_e32 v0, v0
	s_nop 0
	v_add_f32_e32 v0, 1.0, v0
	v_rcp_f32_e32 v67, v0
	s_nop 0
	v_pk_mul_f32 v[50:51], v[66:67], v[56:57]
	s_nop 0
	v_pk_mul_f32 v[34:35], v[34:35], v[50:51]
	v_lshlrev_b32_e32 v50, 16, v55
	v_mul_f32_e32 v0, 0xbfb8aa3b, v50
	v_exp_f32_e32 v0, v0
	v_and_b32_e32 v51, 0xffff0000, v55
	v_cvt_pk_bf16_f32 v34, v34, v35
	v_add_f32_e32 v0, 1.0, v0
	v_rcp_f32_e32 v54, v0
	v_mul_f32_e32 v0, 0xbfb8aa3b, v51
	v_exp_f32_e32 v0, v0
	s_nop 0
	v_add_f32_e32 v0, 1.0, v0
	v_rcp_f32_e32 v55, v0
	s_nop 0
	v_pk_mul_f32 v[50:51], v[54:55], v[50:51]
	s_nop 0
	v_pk_mul_f32 v[36:37], v[36:37], v[50:51]
	s_nop 0
	v_cvt_pk_bf16_f32 v35, v36, v37
	v_mov_b64_e32 v[50:51], v[176:177]
	v_mov_b64_e32 v[52:53], v[178:179]
	v_mov_b64_e32 v[36:37], v[138:139]
	v_pk_mul_f32 v[40:41], v[40:41], v[52:53]
	v_lshlrev_b32_e32 v54, 16, v37
	v_mul_f32_e32 v0, 0xbfb8aa3b, v54
	v_exp_f32_e32 v0, v0
	v_and_b32_e32 v55, 0xffff0000, v37
	v_pk_mul_f32 v[38:39], v[38:39], v[50:51]
	v_add_f32_e32 v0, 1.0, v0
	v_rcp_f32_e32 v56, v0
	v_mul_f32_e32 v0, 0xbfb8aa3b, v55
	v_exp_f32_e32 v0, v0
	s_nop 0
	v_add_f32_e32 v0, 1.0, v0
	v_rcp_f32_e32 v57, v0
	s_nop 0
	v_pk_mul_f32 v[52:53], v[56:57], v[54:55]
	s_nop 0
	v_pk_mul_f32 v[40:41], v[40:41], v[52:53]
	s_nop 0
	v_cvt_pk_bf16_f32 v37, v40, v41
	v_lshlrev_b32_e32 v40, 16, v36
	v_mul_f32_e32 v0, 0xbfb8aa3b, v40
	v_exp_f32_e32 v0, v0
	v_and_b32_e32 v41, 0xffff0000, v36
	v_permlane32_swap_b32_e32 v35, v37
	v_add_f32_e32 v0, 1.0, v0
	v_rcp_f32_e32 v52, v0
	v_mul_f32_e32 v0, 0xbfb8aa3b, v41
	v_exp_f32_e32 v0, v0
	s_nop 0
	v_add_f32_e32 v0, 1.0, v0
	v_rcp_f32_e32 v53, v0
	s_nop 0
	v_pk_mul_f32 v[40:41], v[52:53], v[40:41]
	s_nop 0
	v_pk_mul_f32 v[38:39], v[38:39], v[40:41]
	s_nop 0
	v_cvt_pk_bf16_f32 v36, v38, v39
	s_nop 1
	v_permlane32_swap_b32_e32 v34, v36
	global_store_dwordx4 v[60:61], v[34:37], off offset:64
	s_nop 1
	v_mov_b64_e32 v[38:39], v[140:141]
	s_nop 0
	v_mov_b64_e32 v[34:35], v[180:181]
	v_mov_b64_e32 v[36:37], v[182:183]
	v_lshlrev_b32_e32 v40, 16, v38
	v_mul_f32_e32 v0, 0xbfb8aa3b, v40
	v_exp_f32_e32 v0, v0
	v_and_b32_e32 v41, 0xffff0000, v38
	v_lshlrev_b32_e32 v38, 16, v39
	v_pk_mul_f32 v[34:35], v[42:43], v[34:35]
	v_add_f32_e32 v0, 1.0, v0
	v_rcp_f32_e32 v50, v0
	v_mul_f32_e32 v0, 0xbfb8aa3b, v41
	v_exp_f32_e32 v0, v0
	v_and_b32_e32 v39, 0xffff0000, v39
	v_pk_mul_f32 v[42:43], v[44:45], v[58:59] op_sel_hi:[1,0]
	v_add_f32_e32 v0, 1.0, v0
	v_rcp_f32_e32 v51, v0
	v_mul_f32_e32 v0, 0xbfb8aa3b, v38
	v_exp_f32_e32 v0, v0
	v_pk_mul_f32 v[36:37], v[42:43], v[36:37]
	v_pk_mul_f32 v[40:41], v[50:51], v[40:41]
	v_add_f32_e32 v0, 1.0, v0
	v_pk_mul_f32 v[34:35], v[34:35], v[40:41]
	v_rcp_f32_e32 v40, v0
	v_mul_f32_e32 v0, 0xbfb8aa3b, v39
	v_exp_f32_e32 v0, v0
	v_cvt_pk_bf16_f32 v34, v34, v35
	v_add_f32_e32 v0, 1.0, v0
	v_rcp_f32_e32 v41, v0
	s_nop 0
	v_pk_mul_f32 v[38:39], v[40:41], v[38:39]
	s_nop 0
	v_pk_mul_f32 v[36:37], v[36:37], v[38:39]
	s_nop 0
	v_cvt_pk_bf16_f32 v35, v36, v37
	v_mov_b64_e32 v[38:39], v[184:185]
	v_mov_b64_e32 v[40:41], v[186:187]
	v_mov_b64_e32 v[36:37], v[142:143]
	v_pk_mul_f32 v[40:41], v[48:49], v[40:41]
	v_lshlrev_b32_e32 v42, 16, v37
	v_mul_f32_e32 v0, 0xbfb8aa3b, v42
	v_exp_f32_e32 v0, v0
	v_and_b32_e32 v43, 0xffff0000, v37
	v_add_f32_e32 v0, 1.0, v0
	v_rcp_f32_e32 v44, v0
	v_mul_f32_e32 v0, 0xbfb8aa3b, v43
	v_exp_f32_e32 v0, v0
	s_nop 0
	v_add_f32_e32 v0, 1.0, v0
	v_rcp_f32_e32 v45, v0
	s_nop 0
	v_pk_mul_f32 v[42:43], v[44:45], v[42:43]
	s_nop 0
	v_pk_mul_f32 v[40:41], v[40:41], v[42:43]
	v_pk_mul_f32 v[44:45], v[46:47], v[58:59] op_sel_hi:[1,0]
	v_cvt_pk_bf16_f32 v37, v40, v41
	v_lshlrev_b32_e32 v40, 16, v36
	v_mul_f32_e32 v0, 0xbfb8aa3b, v40
	v_exp_f32_e32 v0, v0
	v_and_b32_e32 v41, 0xffff0000, v36
	v_pk_mul_f32 v[38:39], v[44:45], v[38:39]
	v_permlane32_swap_b32_e32 v35, v37
	v_add_f32_e32 v0, 1.0, v0
	v_rcp_f32_e32 v42, v0
	v_mul_f32_e32 v0, 0xbfb8aa3b, v41
	v_exp_f32_e32 v0, v0
	s_nop 0
	v_add_f32_e32 v0, 1.0, v0
	v_rcp_f32_e32 v43, v0
	s_nop 0
	v_pk_mul_f32 v[40:41], v[42:43], v[40:41]
	s_nop 0
	v_pk_mul_f32 v[38:39], v[38:39], v[40:41]
	s_nop 0
	v_cvt_pk_bf16_f32 v36, v38, v39
	s_nop 1
	v_permlane32_swap_b32_e32 v34, v36
	global_store_dwordx4 v[60:61], v[34:37], off offset:96
	s_nop 1
	v_mov_b64_e32 v[38:39], v[144:145]
; __device__ __forceinline__ unsigned cvtpk(float lo, float hi) { f32x2_t v = {lo, hi}; bf16x2_t b = __builtin_convertvector(v, bf16x2_t); return __builtin_bit_cast(unsigned, b); }
; __device__ __forceinline__ float bf_lo(unsigned w) { return __uint_as_float(w << 16); }
; __device__ __forceinline__ float bf_hi(unsigned w) { return __uint_as_float(w & 0xffff0000u); }
; __device__ __forceinline__ float silu_f(float x) { return x * __builtin_amdgcn_rcpf(1.f + __expf(-x)); }
; template <bool FIXM> __device__ __forceinline__ void diff_unit(int b, int h, int qb, float lam, const bf16* U, const bf16* VTa, bf16* Y, const float* subg, const float* qgain, const int* pos, unsigned char* lds, int tid, int wid, int lane) {
;     ...
; #pragma unroll
;     for (int db = 0; db < 4; ++db)
; #pragma unroll
;         for (int g4 = 0; g4 < 4; ++g4) {
;             const int e = 32 * db + 8 * g4 + 4 * hi_e;
;             const u32x2 gw = *(const u32x2*)(gar + e); const f32x4 sg = *(const f32x4*)(subg + e);
;             const float y0 = o[db][4 * g4 + 0] * rstd * sg.x * silu_f(bf_lo(gw.x)), y1 = o[db][4 * g4 + 1] * rstd * sg.y * silu_f(bf_hi(gw.x));
;             const float y2 = o[db][4 * g4 + 2] * rstd * sg.z * silu_f(bf_lo(gw.y)), y3 = o[db][4 * g4 + 3] * rstd * sg.w * silu_f(bf_hi(gw.y));
;             u32x2 w; w.x = cvtpk(y0, y1); w.y = cvtpk(y2, y3);
;             if ((g4 & 1) == 0) wprev = w; else store_pair16(yr + 32 * db + 16 * (g4 >> 1) + 8 * hi_e, wprev, w);
;         }
	s_nop 0
	v_mov_b64_e32 v[34:35], v[188:189]
	v_mov_b64_e32 v[36:37], v[190:191]
	v_lshlrev_b32_e32 v40, 16, v38
	v_mul_f32_e32 v0, 0xbfb8aa3b, v40
	v_exp_f32_e32 v0, v0
	v_and_b32_e32 v41, 0xffff0000, v38
	v_pk_mul_f32 v[18:19], v[18:19], v[34:35]
	v_pk_mul_f32 v[20:21], v[20:21], v[36:37]
	v_add_f32_e32 v0, 1.0, v0
	v_rcp_f32_e32 v42, v0
	v_mul_f32_e32 v0, 0xbfb8aa3b, v41
	v_exp_f32_e32 v0, v0
	s_nop 0
	v_add_f32_e32 v0, 1.0, v0
	v_rcp_f32_e32 v43, v0
	s_nop 0
	v_pk_mul_f32 v[34:35], v[42:43], v[40:41]
	s_nop 0
	v_pk_mul_f32 v[18:19], v[18:19], v[34:35]
	v_lshlrev_b32_e32 v34, 16, v39
	v_mul_f32_e32 v0, 0xbfb8aa3b, v34
	v_exp_f32_e32 v0, v0
	v_and_b32_e32 v35, 0xffff0000, v39
	v_cvt_pk_bf16_f32 v18, v18, v19
	v_add_f32_e32 v0, 1.0, v0
	v_rcp_f32_e32 v38, v0
	v_mul_f32_e32 v0, 0xbfb8aa3b, v35
	v_exp_f32_e32 v0, v0
	s_nop 0
	v_add_f32_e32 v0, 1.0, v0
	v_rcp_f32_e32 v39, v0
	s_nop 0
	v_pk_mul_f32 v[34:35], v[38:39], v[34:35]
	s_nop 0
	v_pk_mul_f32 v[20:21], v[20:21], v[34:35]
	s_nop 0
	v_cvt_pk_bf16_f32 v19, v20, v21
	v_mov_b64_e32 v[34:35], v[192:193]
	v_mov_b64_e32 v[36:37], v[194:195]
	v_mov_b64_e32 v[20:21], v[146:147]
	v_pk_mul_f32 v[24:25], v[24:25], v[36:37]
	v_lshlrev_b32_e32 v38, 16, v21
	v_mul_f32_e32 v0, 0xbfb8aa3b, v38
	v_exp_f32_e32 v0, v0
	v_and_b32_e32 v39, 0xffff0000, v21
	v_pk_mul_f32 v[22:23], v[22:23], v[34:35]
	v_add_f32_e32 v0, 1.0, v0
	v_rcp_f32_e32 v40, v0
	v_mul_f32_e32 v0, 0xbfb8aa3b, v39
	v_exp_f32_e32 v0, v0
	s_nop 0
	v_add_f32_e32 v0, 1.0, v0
	v_rcp_f32_e32 v41, v0
	s_nop 0
	v_pk_mul_f32 v[36:37], v[40:41], v[38:39]
	s_nop 0
	v_pk_mul_f32 v[24:25], v[24:25], v[36:37]
	s_nop 0
	v_cvt_pk_bf16_f32 v21, v24, v25
	v_lshlrev_b32_e32 v24, 16, v20
	v_mul_f32_e32 v0, 0xbfb8aa3b, v24
	v_exp_f32_e32 v0, v0
	v_and_b32_e32 v25, 0xffff0000, v20
	v_permlane32_swap_b32_e32 v19, v21
	v_add_f32_e32 v0, 1.0, v0
	v_rcp_f32_e32 v36, v0
	v_mul_f32_e32 v0, 0xbfb8aa3b, v25
	v_exp_f32_e32 v0, v0
	s_nop 0
	v_add_f32_e32 v0, 1.0, v0
	v_rcp_f32_e32 v37, v0
	s_nop 0
	v_pk_mul_f32 v[24:25], v[36:37], v[24:25]
	s_nop 0
	v_pk_mul_f32 v[22:23], v[22:23], v[24:25]
	s_nop 0
	v_cvt_pk_bf16_f32 v20, v22, v23
	s_nop 1
	v_permlane32_swap_b32_e32 v18, v20
	global_store_dwordx4 v[60:61], v[18:21], off offset:128
	s_nop 1
	v_mov_b64_e32 v[22:23], v[148:149]
	s_nop 0
	v_mov_b64_e32 v[18:19], v[196:197]
	v_mov_b64_e32 v[20:21], v[198:199]
	v_lshlrev_b32_e32 v24, 16, v22
	v_mul_f32_e32 v0, 0xbfb8aa3b, v24
	v_exp_f32_e32 v0, v0
	v_and_b32_e32 v25, 0xffff0000, v22
	v_lshlrev_b32_e32 v22, 16, v23
	v_pk_mul_f32 v[18:19], v[26:27], v[18:19]
	v_add_f32_e32 v0, 1.0, v0
	v_rcp_f32_e32 v34, v0
	v_mul_f32_e32 v0, 0xbfb8aa3b, v25
	v_exp_f32_e32 v0, v0
	v_and_b32_e32 v23, 0xffff0000, v23
	v_pk_mul_f32 v[26:27], v[28:29], v[58:59] op_sel_hi:[1,0]
	v_add_f32_e32 v0, 1.0, v0
	v_rcp_f32_e32 v35, v0
	v_mul_f32_e32 v0, 0xbfb8aa3b, v22
	v_exp_f32_e32 v0, v0
	v_pk_mul_f32 v[20:21], v[26:27], v[20:21]
	v_pk_mul_f32 v[24:25], v[34:35], v[24:25]
	v_add_f32_e32 v0, 1.0, v0
	v_pk_mul_f32 v[18:19], v[18:19], v[24:25]
	v_rcp_f32_e32 v24, v0
	v_mul_f32_e32 v0, 0xbfb8aa3b, v23
	v_exp_f32_e32 v0, v0
	v_cvt_pk_bf16_f32 v18, v18, v19
	v_add_f32_e32 v0, 1.0, v0
	v_rcp_f32_e32 v25, v0
	s_nop 0
	v_pk_mul_f32 v[22:23], v[24:25], v[22:23]
	s_nop 0
	v_pk_mul_f32 v[20:21], v[20:21], v[22:23]
	s_nop 0
	v_cvt_pk_bf16_f32 v19, v20, v21
	v_mov_b64_e32 v[22:23], v[200:201]
	v_mov_b64_e32 v[24:25], v[202:203]
	v_mov_b64_e32 v[20:21], v[150:151]
	v_pk_mul_f32 v[24:25], v[32:33], v[24:25]
	v_lshlrev_b32_e32 v26, 16, v21
	v_mul_f32_e32 v0, 0xbfb8aa3b, v26
	v_exp_f32_e32 v0, v0
	v_and_b32_e32 v27, 0xffff0000, v21
	v_add_f32_e32 v0, 1.0, v0
	v_rcp_f32_e32 v28, v0
	v_mul_f32_e32 v0, 0xbfb8aa3b, v27
	v_exp_f32_e32 v0, v0
	s_nop 0
	v_add_f32_e32 v0, 1.0, v0
	v_rcp_f32_e32 v29, v0
	s_nop 0
	v_pk_mul_f32 v[26:27], v[28:29], v[26:27]
	s_nop 0
	v_pk_mul_f32 v[24:25], v[24:25], v[26:27]
	v_pk_mul_f32 v[28:29], v[30:31], v[58:59] op_sel_hi:[1,0]
	v_cvt_pk_bf16_f32 v21, v24, v25
	v_lshlrev_b32_e32 v24, 16, v20
	v_mul_f32_e32 v0, 0xbfb8aa3b, v24
	v_exp_f32_e32 v0, v0
	v_and_b32_e32 v25, 0xffff0000, v20
	v_pk_mul_f32 v[22:23], v[28:29], v[22:23]
	v_permlane32_swap_b32_e32 v19, v21
	v_add_f32_e32 v0, 1.0, v0
	v_rcp_f32_e32 v26, v0
	v_mul_f32_e32 v0, 0xbfb8aa3b, v25
	v_exp_f32_e32 v0, v0
	s_nop 0
	v_add_f32_e32 v0, 1.0, v0
	v_rcp_f32_e32 v27, v0
	s_nop 0
	v_pk_mul_f32 v[24:25], v[26:27], v[24:25]
	s_nop 0
	v_pk_mul_f32 v[22:23], v[22:23], v[24:25]
	s_nop 0
	v_cvt_pk_bf16_f32 v20, v22, v23
	s_nop 1
	v_permlane32_swap_b32_e32 v18, v20
; __device__ __forceinline__ unsigned cvtpk(float lo, float hi) { f32x2_t v = {lo, hi}; bf16x2_t b = __builtin_convertvector(v, bf16x2_t); return __builtin_bit_cast(unsigned, b); }
; __device__ __forceinline__ float bf_lo(unsigned w) { return __uint_as_float(w << 16); }
; __device__ __forceinline__ float bf_hi(unsigned w) { return __uint_as_float(w & 0xffff0000u); }
; __device__ __forceinline__ float silu_f(float x) { return x * __builtin_amdgcn_rcpf(1.f + __expf(-x)); }
; template <bool FIXM> __device__ __forceinline__ void diff_unit(int b, int h, int qb, float lam, const bf16* U, const bf16* VTa, bf16* Y, const float* subg, const float* qgain, const int* pos, unsigned char* lds, int tid, int wid, int lane) {
;     ...
; #pragma unroll
;     for (int db = 0; db < 4; ++db)
; #pragma unroll
;         for (int g4 = 0; g4 < 4; ++g4) {
;             const int e = 32 * db + 8 * g4 + 4 * hi_e;
;             const u32x2 gw = *(const u32x2*)(gar + e); const f32x4 sg = *(const f32x4*)(subg + e);
;             const float y0 = o[db][4 * g4 + 0] * rstd * sg.x * silu_f(bf_lo(gw.x)), y1 = o[db][4 * g4 + 1] * rstd * sg.y * silu_f(bf_hi(gw.x));
;             const float y2 = o[db][4 * g4 + 2] * rstd * sg.z * silu_f(bf_lo(gw.y)), y3 = o[db][4 * g4 + 3] * rstd * sg.w * silu_f(bf_hi(gw.y));
;             u32x2 w; w.x = cvtpk(y0, y1); w.y = cvtpk(y2, y3);
;             if ((g4 & 1) == 0) wprev = w; else store_pair16(yr + 32 * db + 16 * (g4 >> 1) + 8 * hi_e, wprev, w);
;         }
	global_store_dwordx4 v[60:61], v[18:21], off offset:160
	s_nop 1
	v_mov_b64_e32 v[22:23], v[152:153]
	s_nop 0
	v_mov_b64_e32 v[18:19], v[204:205]
	v_mov_b64_e32 v[20:21], v[206:207]
	v_lshlrev_b32_e32 v24, 16, v22
	v_mul_f32_e32 v0, 0xbfb8aa3b, v24
	v_exp_f32_e32 v0, v0
	v_and_b32_e32 v25, 0xffff0000, v22
	v_pk_mul_f32 v[2:3], v[2:3], v[18:19]
	v_pk_mul_f32 v[4:5], v[4:5], v[20:21]
	v_add_f32_e32 v0, 1.0, v0
	v_rcp_f32_e32 v26, v0
	v_mul_f32_e32 v0, 0xbfb8aa3b, v25
	v_exp_f32_e32 v0, v0
	s_nop 0
	v_add_f32_e32 v0, 1.0, v0
	v_rcp_f32_e32 v27, v0
	s_nop 0
	v_pk_mul_f32 v[18:19], v[26:27], v[24:25]
	s_nop 0
	v_pk_mul_f32 v[2:3], v[2:3], v[18:19]
	v_lshlrev_b32_e32 v18, 16, v23
	v_mul_f32_e32 v0, 0xbfb8aa3b, v18
	v_exp_f32_e32 v0, v0
	v_and_b32_e32 v19, 0xffff0000, v23
	v_cvt_pk_bf16_f32 v2, v2, v3
	v_add_f32_e32 v0, 1.0, v0
	v_rcp_f32_e32 v22, v0
	v_mul_f32_e32 v0, 0xbfb8aa3b, v19
	v_exp_f32_e32 v0, v0
	s_nop 0
	v_add_f32_e32 v0, 1.0, v0
	v_rcp_f32_e32 v23, v0
	s_nop 0
	v_pk_mul_f32 v[18:19], v[22:23], v[18:19]
	s_nop 0
	v_pk_mul_f32 v[4:5], v[4:5], v[18:19]
	s_nop 0
	v_cvt_pk_bf16_f32 v3, v4, v5
	v_mov_b64_e32 v[18:19], v[208:209]
	v_mov_b64_e32 v[20:21], v[210:211]
	v_mov_b64_e32 v[4:5], v[154:155]
	v_pk_mul_f32 v[8:9], v[8:9], v[20:21]
	v_lshlrev_b32_e32 v22, 16, v5
	v_mul_f32_e32 v0, 0xbfb8aa3b, v22
	v_exp_f32_e32 v0, v0
	v_and_b32_e32 v23, 0xffff0000, v5
	v_pk_mul_f32 v[6:7], v[6:7], v[18:19]
	v_add_f32_e32 v0, 1.0, v0
	v_rcp_f32_e32 v24, v0
	v_mul_f32_e32 v0, 0xbfb8aa3b, v23
	v_exp_f32_e32 v0, v0
	s_nop 0
	v_add_f32_e32 v0, 1.0, v0
	v_rcp_f32_e32 v25, v0
	s_nop 0
	v_pk_mul_f32 v[20:21], v[24:25], v[22:23]
	s_nop 0
	v_pk_mul_f32 v[8:9], v[8:9], v[20:21]
	s_nop 0
	v_cvt_pk_bf16_f32 v5, v8, v9
	v_lshlrev_b32_e32 v8, 16, v4
	v_mul_f32_e32 v0, 0xbfb8aa3b, v8
	v_exp_f32_e32 v0, v0
	v_and_b32_e32 v9, 0xffff0000, v4
	v_permlane32_swap_b32_e32 v3, v5
	v_add_f32_e32 v0, 1.0, v0
	v_rcp_f32_e32 v20, v0
	v_mul_f32_e32 v0, 0xbfb8aa3b, v9
	v_exp_f32_e32 v0, v0
	s_nop 0
	v_add_f32_e32 v0, 1.0, v0
	v_rcp_f32_e32 v21, v0
	s_nop 0
	v_pk_mul_f32 v[8:9], v[20:21], v[8:9]
	s_nop 0
	v_pk_mul_f32 v[6:7], v[6:7], v[8:9]
	s_nop 0
	v_cvt_pk_bf16_f32 v4, v6, v7
	s_nop 1
	v_permlane32_swap_b32_e32 v2, v4
	global_store_dwordx4 v[60:61], v[2:5], off offset:192
	s_nop 1
	v_mov_b64_e32 v[6:7], v[156:157]
	s_nop 0
	v_mov_b64_e32 v[2:3], v[212:213]
	v_mov_b64_e32 v[4:5], v[214:215]
	v_lshlrev_b32_e32 v8, 16, v6
	v_mul_f32_e32 v0, 0xbfb8aa3b, v8
	v_exp_f32_e32 v0, v0
	v_and_b32_e32 v9, 0xffff0000, v6
	v_lshlrev_b32_e32 v6, 16, v7
	v_pk_mul_f32 v[2:3], v[10:11], v[2:3]
	v_add_f32_e32 v0, 1.0, v0
	v_rcp_f32_e32 v18, v0
	v_mul_f32_e32 v0, 0xbfb8aa3b, v9
	v_exp_f32_e32 v0, v0
	v_and_b32_e32 v7, 0xffff0000, v7
	v_pk_mul_f32 v[10:11], v[12:13], v[58:59] op_sel_hi:[1,0]
	v_add_f32_e32 v0, 1.0, v0
	v_rcp_f32_e32 v19, v0
	v_mul_f32_e32 v0, 0xbfb8aa3b, v6
	v_exp_f32_e32 v0, v0
	v_pk_mul_f32 v[4:5], v[10:11], v[4:5]
	v_pk_mul_f32 v[8:9], v[18:19], v[8:9]
	v_add_f32_e32 v0, 1.0, v0
	v_pk_mul_f32 v[2:3], v[2:3], v[8:9]
	v_rcp_f32_e32 v8, v0
	v_mul_f32_e32 v0, 0xbfb8aa3b, v7
	v_exp_f32_e32 v0, v0
	v_cvt_pk_bf16_f32 v2, v2, v3
	v_add_f32_e32 v0, 1.0, v0
	v_rcp_f32_e32 v9, v0
	s_nop 0
	v_pk_mul_f32 v[6:7], v[8:9], v[6:7]
	s_nop 0
	v_pk_mul_f32 v[4:5], v[4:5], v[6:7]
	s_nop 0
	v_cvt_pk_bf16_f32 v3, v4, v5
	v_mov_b64_e32 v[6:7], v[216:217]
	v_mov_b64_e32 v[8:9], v[218:219]
	v_mov_b64_e32 v[4:5], v[158:159]
	v_pk_mul_f32 v[8:9], v[16:17], v[8:9]
	v_lshlrev_b32_e32 v10, 16, v5
	v_mul_f32_e32 v0, 0xbfb8aa3b, v10
	v_exp_f32_e32 v0, v0
	v_and_b32_e32 v11, 0xffff0000, v5
	v_add_f32_e32 v0, 1.0, v0
	v_rcp_f32_e32 v12, v0
	v_mul_f32_e32 v0, 0xbfb8aa3b, v11
	v_exp_f32_e32 v0, v0
	s_nop 0
	v_add_f32_e32 v0, 1.0, v0
	v_rcp_f32_e32 v13, v0
	s_nop 0
	v_pk_mul_f32 v[10:11], v[12:13], v[10:11]
	s_nop 0
	v_pk_mul_f32 v[8:9], v[8:9], v[10:11]
	v_pk_mul_f32 v[12:13], v[14:15], v[58:59] op_sel_hi:[1,0]
	v_cvt_pk_bf16_f32 v5, v8, v9
	v_lshlrev_b32_e32 v8, 16, v4
	v_mul_f32_e32 v0, 0xbfb8aa3b, v8
	v_exp_f32_e32 v0, v0
	v_and_b32_e32 v9, 0xffff0000, v4
	v_pk_mul_f32 v[6:7], v[12:13], v[6:7]
	v_permlane32_swap_b32_e32 v3, v5
	v_add_f32_e32 v0, 1.0, v0
	v_rcp_f32_e32 v10, v0
	v_mul_f32_e32 v0, 0xbfb8aa3b, v9
	v_exp_f32_e32 v0, v0
	s_nop 0
	v_add_f32_e32 v0, 1.0, v0
	v_rcp_f32_e32 v11, v0
	s_nop 0
	v_pk_mul_f32 v[8:9], v[10:11], v[8:9]
	s_nop 0
	v_pk_mul_f32 v[6:7], v[6:7], v[8:9]
	s_nop 0
	v_cvt_pk_bf16_f32 v4, v6, v7
	s_nop 1
	v_permlane32_swap_b32_e32 v2, v4
	global_store_dwordx4 v[60:61], v[2:5], off offset:224
	s_nop 1
